# E phases: 16-byte f32 row loads also with default cache policy (on top of default-policy 8-byte loads)
# speedup vs baseline: 1.0059x; 1.0059x over previous
; DI void phase_e(const Ctx& C, int nslab, int has_post, int pl, int ps, float pw, int has_pre, int ql, int qs, int nrows,
;                 const GAS float* xsrc, const GAS float* csrc, GAS float* xdst, GAS float* cdst, bool xs16, bool xd16) {
;     ...
;     if (i < total) E_LOAD(i, vN, yN);
;     if (i + 8 < total) E_LOAD(i + 8, vM, yM);
.LBB0_180:
	s_add_i32 s4, s13, 0xffff8000
	s_ashr_i32 s5, s13, 31
	s_cmp_lt_i32 s13, 0x8000
	s_cselect_b32 s5, s5, 0
	s_cselect_b32 s4, s13, s4
	s_cselect_b32 s13, s37, s41
	s_cselect_b32 s22, s36, s40
	s_lshl_b64 s[4:5], s[4:5], 12
	s_add_u32 s4, s22, s4
	s_addc_u32 s5, s13, s5
	global_load_dwordx4 v[46:49], v98, s[4:5]
	global_load_dwordx4 v[26:29], v98, s[4:5] offset:1024
	global_load_dwordx4 v[22:25], v98, s[4:5] offset:2048
	global_load_dwordx4 v[18:21], v98, s[4:5] offset:3072

; DI void phase_e(const Ctx& C, int nslab, int has_post, int pl, int ps, float pw, int has_pre, int ql, int qs, int nrows,
;                 const GAS float* xsrc, const GAS float* csrc, GAS float* xdst, GAS float* cdst, bool xs16, bool xd16) {
;     ...
;     if (i + 8 < total) E_LOAD(i + 8, vM, yM);
.LBB0_187:
	s_add_i32 s4, s22, 0xffff8000
	s_ashr_i32 s5, s22, 31
	s_cmp_lt_i32 s22, 0x8000
	s_cselect_b32 s5, s5, 0
	s_cselect_b32 s4, s22, s4
	s_cselect_b32 s13, s37, s41
	s_cselect_b32 s22, s36, s40
	s_lshl_b64 s[4:5], s[4:5], 12
	s_add_u32 s4, s22, s4
	s_addc_u32 s5, s13, s5
	global_load_dwordx4 v[30:33], v98, s[4:5]
	global_load_dwordx4 v[34:37], v98, s[4:5] offset:1024
	global_load_dwordx4 v[38:41], v98, s[4:5] offset:2048
	global_load_dwordx4 v[42:45], v98, s[4:5] offset:3072
	s_andn2_b64 vcc, exec, s[2:3]
	s_cbranch_vccnz .LBB0_194

; DI void phase_e(const Ctx& C, int nslab, int has_post, int pl, int ps, float pw, int has_pre, int ql, int qs, int nrows,
;                 const GAS float* xsrc, const GAS float* csrc, GAS float* xdst, GAS float* cdst, bool xs16, bool xd16) {
;     ...
;         if (i + 16 < total) E_LOAD(i + 16, vM, yM);
.LBB0_190:
	s_add_i32 s2, s6, 16
	s_cmp_ge_i32 s2, s8
	s_cbranch_scc1 .LBB0_192
	s_add_i32 s23, s11, s6
	s_add_i32 s3, s12, s6
	s_add_i32 s23, s23, 0x8010
	s_cmp_lt_i32 s2, s7
	s_cselect_b32 s2, s3, s23
	s_add_i32 s23, s2, 0xffff8000
	s_ashr_i32 s3, s2, 31
	s_cmp_lt_i32 s2, 0x8000
	s_cselect_b32 s3, s3, 0
	s_cselect_b32 s2, s2, s23
	s_cselect_b32 s23, s37, s41
	s_cselect_b32 s24, s36, s40
	s_lshl_b64 s[2:3], s[2:3], 12
	s_add_u32 s2, s24, s2
	s_addc_u32 s3, s23, s3
	global_load_dwordx4 v[94:97], v98, s[2:3]
	global_load_dwordx4 v[90:93], v98, s[2:3] offset:1024
	global_load_dwordx4 v[86:89], v98, s[2:3] offset:2048
	global_load_dwordx4 v[82:85], v98, s[2:3] offset:3072

; DI void phase_e(const Ctx& C, int nslab, int has_post, int pl, int ps, float pw, int has_pre, int ql, int qs, int nrows,
;                 const GAS float* xsrc, const GAS float* csrc, GAS float* xdst, GAS float* cdst, bool xs16, bool xd16) {
;     ...
;         if (i + 16 < total) E_LOAD(i + 16, vM, yM);
.Lrow1_190:
	s_add_i32 s2, s6, 16
	s_cmp_ge_i32 s2, s8
	s_cbranch_scc1 .Lrow1_192
	s_add_i32 s23, s11, s6
	s_add_i32 s3, s12, s6
	s_add_i32 s23, s23, 0x8010
	s_cmp_lt_i32 s2, s7
	s_cselect_b32 s2, s3, s23
	s_add_i32 s23, s2, 0xffff8000
	s_ashr_i32 s3, s2, 31
	s_cmp_lt_i32 s2, 0x8000
	s_cselect_b32 s3, s3, 0
	s_cselect_b32 s2, s2, s23
	s_cselect_b32 s23, s37, s41
	s_cselect_b32 s24, s36, s40
	s_lshl_b64 s[2:3], s[2:3], 12
	s_add_u32 s2, s24, s2
	s_addc_u32 s3, s23, s3
	global_load_dwordx4 v[46:49], v98, s[2:3]
	global_load_dwordx4 v[26:29], v98, s[2:3] offset:1024
	global_load_dwordx4 v[86:89], v98, s[2:3] offset:2048
	global_load_dwordx4 v[18:21], v98, s[2:3] offset:3072

; DI void phase_e(const Ctx& C, int nslab, int has_post, int pl, int ps, float pw, int has_pre, int ql, int qs, int nrows,
;                 const GAS float* xsrc, const GAS float* csrc, GAS float* xdst, GAS float* cdst, bool xs16, bool xd16) {
;     ...
;         if (i + 16 < total) E_LOAD(i + 16, vM, yM);
.Lrow2_190:
	s_add_i32 s2, s6, 16
	s_cmp_ge_i32 s2, s8
	s_cbranch_scc1 .Lrow2_192
	s_add_i32 s23, s11, s6
	s_add_i32 s3, s12, s6
	s_add_i32 s23, s23, 0x8010
	s_cmp_lt_i32 s2, s7
	s_cselect_b32 s2, s3, s23
	s_add_i32 s23, s2, 0xffff8000
	s_ashr_i32 s3, s2, 31
	s_cmp_lt_i32 s2, 0x8000
	s_cselect_b32 s3, s3, 0
	s_cselect_b32 s2, s2, s23
	s_cselect_b32 s23, s37, s41
	s_cselect_b32 s24, s36, s40
	s_lshl_b64 s[2:3], s[2:3], 12
	s_add_u32 s2, s24, s2
	s_addc_u32 s3, s23, s3
	global_load_dwordx4 v[30:33], v98, s[2:3]
	global_load_dwordx4 v[34:37], v98, s[2:3] offset:1024
	global_load_dwordx4 v[86:89], v98, s[2:3] offset:2048
	global_load_dwordx4 v[42:45], v98, s[2:3] offset:3072

; DI void phase_e(const Ctx& C, int nslab, int has_post, int pl, int ps, float pw, int has_pre, int ql, int qs, int nrows,
;                 const GAS float* xsrc, const GAS float* csrc, GAS float* xdst, GAS float* cdst, bool xs16, bool xd16) {
;     ...
;     if (i < total) E_LOAD(i, vN, yN);
.LBB0_412:
	s_add_i32 s10, s8, 0xffff8000
	s_ashr_i32 s9, s8, 31
	s_cmp_lt_i32 s8, 0x8000
	s_cselect_b32 s11, s9, 0
	s_cselect_b32 s10, s8, s10
	s_cselect_b32 s28, s37, s41
	s_cselect_b32 s29, s36, s40
	s_lshl_b64 s[10:11], s[10:11], 12
	s_add_u32 s10, s29, s10
	s_addc_u32 s11, s28, s11
	global_load_dwordx4 v[126:129], v142, s[10:11]
	global_load_dwordx4 v[58:61], v142, s[10:11] offset:1024
	global_load_dwordx4 v[54:57], v142, s[10:11] offset:2048
	global_load_dwordx4 v[50:53], v142, s[10:11] offset:3072
	s_cmpk_gt_i32 s8, 0x7fff
	s_cbranch_scc1 .LBB0_414
	s_lshl_b64 s[8:9], s[8:9], 11
	s_add_u32 s8, s2, s8
	s_addc_u32 s9, s3, s9
	v_lshlrev_b32_e32 v34, 1, v62
	global_load_dwordx2 v[170:171], v34, s[8:9]
	global_load_dwordx2 v[134:135], v34, s[8:9] offset:512
	global_load_dwordx2 v[132:133], v34, s[8:9] offset:1024
	global_load_dwordx2 v[130:131], v34, s[8:9] offset:1536

; DI void phase_e(const Ctx& C, int nslab, int has_post, int pl, int ps, float pw, int has_pre, int ql, int qs, int nrows,
;                 const GAS float* xsrc, const GAS float* csrc, GAS float* xdst, GAS float* cdst, bool xs16, bool xd16) {
;     ...
;     if (i + 8 < total) E_LOAD(i + 8, vM, yM);
.LBB0_420:
	s_add_i32 s10, s8, 0xffff8000
	s_ashr_i32 s9, s8, 31
	s_cmp_lt_i32 s8, 0x8000
	s_cselect_b32 s11, s9, 0
	s_cselect_b32 s10, s8, s10
	s_cselect_b32 s28, s37, s41
	s_cselect_b32 s29, s36, s40
	s_lshl_b64 s[10:11], s[10:11], 12
	s_add_u32 s10, s29, s10
	s_addc_u32 s11, s28, s11
	global_load_dwordx4 v[34:37], v142, s[10:11]
	global_load_dwordx4 v[38:41], v142, s[10:11] offset:1024
	global_load_dwordx4 v[42:45], v142, s[10:11] offset:2048
	global_load_dwordx4 v[46:49], v142, s[10:11] offset:3072
	s_cmpk_gt_i32 s8, 0x7fff
	s_cbranch_scc1 .LBB0_422
	s_lshl_b64 s[8:9], s[8:9], 11
	s_add_u32 s8, s2, s8
	s_addc_u32 s9, s3, s9
	v_lshlrev_b32_e32 v63, 1, v62
	global_load_dwordx2 v[144:145], v63, s[8:9]
	global_load_dwordx2 v[146:147], v63, s[8:9] offset:512
	global_load_dwordx2 v[148:149], v63, s[8:9] offset:1024
	global_load_dwordx2 v[150:151], v63, s[8:9] offset:1536

; DI void phase_e(const Ctx& C, int nslab, int has_post, int pl, int ps, float pw, int has_pre, int ql, int qs, int nrows,
;                 const GAS float* xsrc, const GAS float* csrc, GAS float* xdst, GAS float* cdst, bool xs16, bool xd16) {
;     ...
;         for (int j = 0; j < 4; ++j) { v[j] = vN[j]; yw[j] = yN[j]; vN[j] = vM[j]; yN[j] = yM[j]; }
;         if (i + 16 < total) E_LOAD(i + 16, vM, yM);
.LBB0_425:
	s_cmp_ge_i32 s43, s27
	s_cbranch_scc1 .LBB0_428
	s_add_i32 s1, s42, s43
	s_add_i32 s0, s39, s43
	s_add_i32 s1, s1, 0x8000
	s_cmp_lt_i32 s43, s26
	s_cselect_b32 s0, s0, s1
	s_add_i32 s2, s0, 0xffff8000
	s_ashr_i32 s1, s0, 31
	v_readlane_b32 s80, v237, 22
	s_cmp_lt_i32 s0, 0x8000
	v_readlane_b32 s81, v237, 23
	v_readlane_b32 s84, v237, 26
	v_readlane_b32 s85, v237, 27
	s_cselect_b32 s3, s1, 0
	s_cselect_b32 s2, s0, s2
	s_mov_b64 s[36:37], s[80:81]
	s_mov_b64 s[40:41], s[84:85]
	s_cselect_b32 s6, s37, s41
	s_cselect_b32 s12, s36, s40
	s_lshl_b64 s[2:3], s[2:3], 12
	s_add_u32 s2, s12, s2
	s_addc_u32 s3, s6, s3
	global_load_dwordx4 v[122:125], v142, s[2:3]
	global_load_dwordx4 v[118:121], v142, s[2:3] offset:1024
	global_load_dwordx4 v[114:117], v142, s[2:3] offset:2048
	global_load_dwordx4 v[110:113], v142, s[2:3] offset:3072
	s_cmpk_gt_i32 s0, 0x7fff
	v_mov_b64_e32 v[162:163], v[144:145]
	v_mov_b64_e32 v[164:165], v[146:147]
	v_mov_b64_e32 v[166:167], v[148:149]
	v_mov_b64_e32 v[168:169], v[150:151]
	v_readlane_b32 s82, v237, 24
	v_readlane_b32 s83, v237, 25
	v_readlane_b32 s86, v237, 28
	v_readlane_b32 s87, v237, 29
	v_readlane_b32 s88, v237, 30
	v_readlane_b32 s89, v237, 31
	v_readlane_b32 s90, v237, 32
	v_readlane_b32 s91, v237, 33
	v_readlane_b32 s92, v237, 34
	v_readlane_b32 s93, v237, 35
	v_readlane_b32 s94, v237, 36
	v_readlane_b32 s95, v237, 37
	s_cbranch_scc1 .LBB0_428
	s_lshl_b64 s[0:1], s[0:1], 11
	v_lshl_add_u64 v[136:137], v[152:153], 0, s[0:1]
	global_load_dwordx2 v[162:163], v[136:137], off
	global_load_dwordx2 v[164:165], v[136:137], off offset:512
	global_load_dwordx2 v[166:167], v[136:137], off offset:1024
	global_load_dwordx2 v[168:169], v[136:137], off offset:1536

; DI void phase_e(const Ctx& C, int nslab, int has_post, int pl, int ps, float pw, int has_pre, int ql, int qs, int nrows,
;                 const GAS float* xsrc, const GAS float* csrc, GAS float* xdst, GAS float* cdst, bool xs16, bool xd16) {
;     ...
;         for (int j = 0; j < 4; ++j) { v[j] = vN[j]; yw[j] = yN[j]; vN[j] = vM[j]; yN[j] = yM[j]; }
;         if (i + 16 < total) E_LOAD(i + 16, vM, yM);
.Lrow1_425:
	s_cmp_ge_i32 s43, s27
	s_cbranch_scc1 .Lrow1_428
	s_add_i32 s1, s42, s43
	s_add_i32 s0, s39, s43
	s_add_i32 s1, s1, 0x8000
	s_cmp_lt_i32 s43, s26
	s_cselect_b32 s0, s0, s1
	s_add_i32 s2, s0, 0xffff8000
	s_ashr_i32 s1, s0, 31
	v_readlane_b32 s80, v237, 22
	s_cmp_lt_i32 s0, 0x8000
	v_readlane_b32 s81, v237, 23
	v_readlane_b32 s84, v237, 26
	v_readlane_b32 s85, v237, 27
	s_cselect_b32 s3, s1, 0
	s_cselect_b32 s2, s0, s2
	s_mov_b64 s[36:37], s[80:81]
	s_mov_b64 s[40:41], s[84:85]
	s_cselect_b32 s6, s37, s41
	s_cselect_b32 s12, s36, s40
	s_lshl_b64 s[2:3], s[2:3], 12
	s_add_u32 s2, s12, s2
	s_addc_u32 s3, s6, s3
	global_load_dwordx4 v[126:129], v142, s[2:3]
	global_load_dwordx4 v[58:61], v142, s[2:3] offset:1024
	global_load_dwordx4 v[54:57], v142, s[2:3] offset:2048
	global_load_dwordx4 v[50:53], v142, s[2:3] offset:3072
	s_cmpk_gt_i32 s0, 0x7fff
	v_mov_b64_e32 v[162:163], v[144:145]
	v_mov_b64_e32 v[164:165], v[146:147]
	v_mov_b64_e32 v[166:167], v[148:149]
	v_mov_b64_e32 v[168:169], v[150:151]
	v_readlane_b32 s82, v237, 24
	v_readlane_b32 s83, v237, 25
	v_readlane_b32 s86, v237, 28
	v_readlane_b32 s87, v237, 29
	v_readlane_b32 s88, v237, 30
	v_readlane_b32 s89, v237, 31
	v_readlane_b32 s90, v237, 32
	v_readlane_b32 s91, v237, 33
	v_readlane_b32 s92, v237, 34
	v_readlane_b32 s93, v237, 35
	v_readlane_b32 s94, v237, 36
	v_readlane_b32 s95, v237, 37
	s_cbranch_scc1 .Lrow1_428
	s_lshl_b64 s[0:1], s[0:1], 11
	v_lshl_add_u64 v[136:137], v[152:153], 0, s[0:1]
	global_load_dwordx2 v[162:163], v[136:137], off
	global_load_dwordx2 v[164:165], v[136:137], off offset:512
	global_load_dwordx2 v[166:167], v[136:137], off offset:1024
	global_load_dwordx2 v[168:169], v[136:137], off offset:1536

; DI void phase_e(const Ctx& C, int nslab, int has_post, int pl, int ps, float pw, int has_pre, int ql, int qs, int nrows,
;                 const GAS float* xsrc, const GAS float* csrc, GAS float* xdst, GAS float* cdst, bool xs16, bool xd16) {
;     ...
;         for (int j = 0; j < 4; ++j) { v[j] = vN[j]; yw[j] = yN[j]; vN[j] = vM[j]; yN[j] = yM[j]; }
;         if (i + 16 < total) E_LOAD(i + 16, vM, yM);
.Lrow2_425:
	s_cmp_ge_i32 s43, s27
	s_cbranch_scc1 .Lrow2_428
	s_add_i32 s1, s42, s43
	s_add_i32 s0, s39, s43
	s_add_i32 s1, s1, 0x8000
	s_cmp_lt_i32 s43, s26
	s_cselect_b32 s0, s0, s1
	s_add_i32 s2, s0, 0xffff8000
	s_ashr_i32 s1, s0, 31
	v_readlane_b32 s80, v237, 22
	s_cmp_lt_i32 s0, 0x8000
	v_readlane_b32 s81, v237, 23
	v_readlane_b32 s84, v237, 26
	v_readlane_b32 s85, v237, 27
	s_cselect_b32 s3, s1, 0
	s_cselect_b32 s2, s0, s2
	s_mov_b64 s[36:37], s[80:81]
	s_mov_b64 s[40:41], s[84:85]
	s_cselect_b32 s6, s37, s41
	s_cselect_b32 s12, s36, s40
	s_lshl_b64 s[2:3], s[2:3], 12
	s_add_u32 s2, s12, s2
	s_addc_u32 s3, s6, s3
	global_load_dwordx4 v[34:37], v142, s[2:3]
	global_load_dwordx4 v[38:41], v142, s[2:3] offset:1024
	global_load_dwordx4 v[42:45], v142, s[2:3] offset:2048
	global_load_dwordx4 v[46:49], v142, s[2:3] offset:3072
	s_cmpk_gt_i32 s0, 0x7fff
	v_mov_b64_e32 v[162:163], v[144:145]
	v_mov_b64_e32 v[164:165], v[146:147]
	v_mov_b64_e32 v[166:167], v[148:149]
	v_mov_b64_e32 v[168:169], v[150:151]
	v_readlane_b32 s82, v237, 24
	v_readlane_b32 s83, v237, 25
	v_readlane_b32 s86, v237, 28
	v_readlane_b32 s87, v237, 29
	v_readlane_b32 s88, v237, 30
	v_readlane_b32 s89, v237, 31
	v_readlane_b32 s90, v237, 32
	v_readlane_b32 s91, v237, 33
	v_readlane_b32 s92, v237, 34
	v_readlane_b32 s93, v237, 35
	v_readlane_b32 s94, v237, 36
	v_readlane_b32 s95, v237, 37
	s_cbranch_scc1 .Lrow2_428
	s_lshl_b64 s[0:1], s[0:1], 11
	v_lshl_add_u64 v[136:137], v[152:153], 0, s[0:1]
	global_load_dwordx2 v[162:163], v[136:137], off
	global_load_dwordx2 v[164:165], v[136:137], off offset:512
	global_load_dwordx2 v[166:167], v[136:137], off offset:1024
	global_load_dwordx2 v[168:169], v[136:137], off offset:1536

; DI void phase_e(const Ctx& C, int nslab, int has_post, int pl, int ps, float pw, int has_pre, int ql, int qs, int nrows,
;                 const GAS float* xsrc, const GAS float* csrc, GAS float* xdst, GAS float* cdst, bool xs16, bool xd16) {
;     ...
;     if (i < total) E_LOAD(i, vN, yN);
;     if (i + 8 < total) E_LOAD(i + 8, vM, yM);
.LBB0_926:
	s_cmp_lt_i32 s10, 0x8000
	s_cselect_b64 s[12:13], -1, 0
	s_cmpk_gt_i32 s10, 0x7fff
	s_cbranch_scc0 .LBB0_928
	s_add_i32 s14, s10, 0xffff8000
	s_mov_b32 s15, 0
	s_lshl_b64 s[14:15], s[14:15], 12
	s_add_u32 s14, s4, s14
	s_addc_u32 s15, s5, s15
	global_load_dwordx4 v[78:81], v142, s[14:15]
	global_load_dwordx4 v[58:61], v142, s[14:15] offset:1024
	global_load_dwordx4 v[54:57], v142, s[14:15] offset:2048
	global_load_dwordx4 v[46:49], v142, s[14:15] offset:3072
	s_cbranch_execz .LBB0_929
	s_branch .LBB0_930

; DI void phase_e(const Ctx& C, int nslab, int has_post, int pl, int ps, float pw, int has_pre, int ql, int qs, int nrows,
;                 const GAS float* xsrc, const GAS float* csrc, GAS float* xdst, GAS float* cdst, bool xs16, bool xd16) {
;     ...
;     if (i < total) E_LOAD(i, vN, yN);
;     if (i + 8 < total) E_LOAD(i + 8, vM, yM);
.LBB0_937:
	s_cmp_lt_i32 s10, 0x8000
	s_cselect_b64 s[12:13], -1, 0
	s_cmpk_gt_i32 s10, 0x7fff
	s_cbranch_scc0 .LBB0_939
	s_add_i32 s14, s10, 0xffff8000
	s_mov_b32 s15, 0
	s_lshl_b64 s[14:15], s[14:15], 12
	s_add_u32 s14, s4, s14
	s_addc_u32 s15, s5, s15
	global_load_dwordx4 v[34:37], v142, s[14:15]
	global_load_dwordx4 v[38:41], v142, s[14:15] offset:1024
	global_load_dwordx4 v[42:45], v142, s[14:15] offset:2048
	global_load_dwordx4 v[50:53], v142, s[14:15] offset:3072
	s_cbranch_execz .LBB0_940
	s_branch .LBB0_941

; DI void phase_e(const Ctx& C, int nslab, int has_post, int pl, int ps, float pw, int has_pre, int ql, int qs, int nrows,
;                 const GAS float* xsrc, const GAS float* csrc, GAS float* xdst, GAS float* cdst, bool xs16, bool xd16) {
;     ...
;         if (i + 16 < total) E_LOAD(i + 16, vM, yM);
.LBB0_946:
	s_mov_b64 s[98:99], 0
	s_cmp_ge_i32 s23, s17
	s_cbranch_scc1 .LBB0_953
	s_add_i32 s1, s22, s23
	s_add_i32 s0, s21, s23
	s_add_i32 s1, s1, 0x8000
	s_cmp_lt_i32 s23, s16
	s_cselect_b32 s0, s0, s1
	s_cmp_lt_i32 s0, 0x8000
	s_cselect_b64 s[2:3], -1, 0
	s_cmpk_gt_i32 s0, 0x7fff
	s_mov_b64 s[10:11], -1
	s_cbranch_scc0 .LBB0_949
	s_add_i32 s4, s0, 0xffff8000
	s_lshl_b64 s[10:11], s[4:5], 12
	v_lshl_add_u64 v[126:127], v[160:161], 0, s[10:11]
	global_load_dwordx4 v[114:117], v[126:127], off
	global_load_dwordx4 v[118:121], v[126:127], off offset:1024
	global_load_dwordx4 v[122:125], v[126:127], off offset:2048
	s_nop 0
	global_load_dwordx4 v[126:129], v[126:127], off offset:3072
	s_mov_b64 s[10:11], 0

; DI void phase_e(const Ctx& C, int nslab, int has_post, int pl, int ps, float pw, int has_pre, int ql, int qs, int nrows,
;                 const GAS float* xsrc, const GAS float* csrc, GAS float* xdst, GAS float* cdst, bool xs16, bool xd16) {
;     ...
;         if (i + 16 < total) E_LOAD(i + 16, vM, yM);
.Lrow1_946:
	s_mov_b64 s[98:99], 0
	s_cmp_ge_i32 s23, s17
	s_cbranch_scc1 .Lrow1_953
	s_add_i32 s1, s22, s23
	s_add_i32 s0, s21, s23
	s_add_i32 s1, s1, 0x8000
	s_cmp_lt_i32 s23, s16
	s_cselect_b32 s0, s0, s1
	s_cmp_lt_i32 s0, 0x8000
	s_cselect_b64 s[2:3], -1, 0
	s_cmpk_gt_i32 s0, 0x7fff
	s_mov_b64 s[10:11], -1
	s_cbranch_scc0 .Lrow1_949
	s_add_i32 s4, s0, 0xffff8000
	s_lshl_b64 s[10:11], s[4:5], 12
	v_lshl_add_u64 v[46:47], v[160:161], 0, s[10:11]
	global_load_dwordx4 v[78:81], v[46:47], off
	global_load_dwordx4 v[58:61], v[46:47], off offset:1024
	global_load_dwordx4 v[54:57], v[46:47], off offset:2048
	s_nop 0
	global_load_dwordx4 v[46:49], v[46:47], off offset:3072
	s_mov_b64 s[10:11], 0

; DI void phase_e(const Ctx& C, int nslab, int has_post, int pl, int ps, float pw, int has_pre, int ql, int qs, int nrows,
;                 const GAS float* xsrc, const GAS float* csrc, GAS float* xdst, GAS float* cdst, bool xs16, bool xd16) {
;     ...
;         if (i + 16 < total) E_LOAD(i + 16, vM, yM);
.Lrow2_946:
	s_mov_b64 s[98:99], 0
	s_cmp_ge_i32 s23, s17
	s_cbranch_scc1 .Lrow2_953
	s_add_i32 s1, s22, s23
	s_add_i32 s0, s21, s23
	s_add_i32 s1, s1, 0x8000
	s_cmp_lt_i32 s23, s16
	s_cselect_b32 s0, s0, s1
	s_cmp_lt_i32 s0, 0x8000
	s_cselect_b64 s[2:3], -1, 0
	s_cmpk_gt_i32 s0, 0x7fff
	s_mov_b64 s[10:11], -1
	s_cbranch_scc0 .Lrow2_949
	s_add_i32 s4, s0, 0xffff8000
	s_lshl_b64 s[10:11], s[4:5], 12
	v_lshl_add_u64 v[50:51], v[160:161], 0, s[10:11]
	global_load_dwordx4 v[34:37], v[50:51], off
	global_load_dwordx4 v[38:41], v[50:51], off offset:1024
	global_load_dwordx4 v[42:45], v[50:51], off offset:2048
	s_nop 0
	global_load_dwordx4 v[50:53], v[50:51], off offset:3072
	s_mov_b64 s[10:11], 0

; DI void phase_e(const Ctx& C, int nslab, int has_post, int pl, int ps, float pw, int has_pre, int ql, int qs, int nrows,
;                 const GAS float* xsrc, const GAS float* csrc, GAS float* xdst, GAS float* cdst, bool xs16, bool xd16) {
;     ...
;     if (i < total) E_LOAD(i, vN, yN);
.LBB0_1193:
	s_cmp_lt_i32 s10, 0x8000
	s_cselect_b64 s[12:13], -1, 0
	s_cmpk_gt_i32 s10, 0x7fff
	s_cbranch_scc0 .LBB0_1195
	s_add_i32 s14, s10, 0xffff8000
	s_mov_b32 s15, 0
	s_lshl_b64 s[14:15], s[14:15], 12
	s_add_u32 s14, s4, s14
	s_addc_u32 s15, s5, s15
	global_load_dwordx4 v[98:101], v142, s[14:15]
	global_load_dwordx4 v[58:61], v142, s[14:15] offset:1024
	global_load_dwordx4 v[54:57], v142, s[14:15] offset:2048
	global_load_dwordx4 v[46:49], v142, s[14:15] offset:3072
	s_cbranch_execz .LBB0_1196
	s_branch .LBB0_1197

; DI void phase_e(const Ctx& C, int nslab, int has_post, int pl, int ps, float pw, int has_pre, int ql, int qs, int nrows,
;                 const GAS float* xsrc, const GAS float* csrc, GAS float* xdst, GAS float* cdst, bool xs16, bool xd16) {
;     ...
;         if (i + 16 < total) E_LOAD(i + 16, vM, yM);
.LBB0_1213:
	s_mov_b64 s[98:99], 0
	s_cmp_ge_i32 s22, s17
	s_cbranch_scc1 .LBB0_1220
	s_add_i32 s1, s21, s22
	s_add_i32 s0, s20, s22
	s_add_i32 s1, s1, 0x8000
	s_cmp_lt_i32 s22, s16
	s_cselect_b32 s0, s0, s1
	s_cmp_lt_i32 s0, 0x8000
	s_cselect_b64 s[2:3], -1, 0
	s_cmpk_gt_i32 s0, 0x7fff
	s_mov_b64 s[10:11], -1
	s_cbranch_scc0 .LBB0_1216
	s_add_i32 s4, s0, 0xffff8000
	s_lshl_b64 s[10:11], s[4:5], 12
	v_lshl_add_u64 v[126:127], v[160:161], 0, s[10:11]
	global_load_dwordx4 v[114:117], v[126:127], off
	global_load_dwordx4 v[118:121], v[126:127], off offset:1024
	global_load_dwordx4 v[122:125], v[126:127], off offset:2048
	s_nop 0
	global_load_dwordx4 v[126:129], v[126:127], off offset:3072
	s_mov_b64 s[10:11], 0

; DI void phase_e(const Ctx& C, int nslab, int has_post, int pl, int ps, float pw, int has_pre, int ql, int qs, int nrows,
;                 const GAS float* xsrc, const GAS float* csrc, GAS float* xdst, GAS float* cdst, bool xs16, bool xd16) {
;     ...
;         if (i + 16 < total) E_LOAD(i + 16, vM, yM);
.Lrow1_1213:
	s_mov_b64 s[98:99], 0
	s_cmp_ge_i32 s22, s17
	s_cbranch_scc1 .Lrow1_1220
	s_add_i32 s1, s21, s22
	s_add_i32 s0, s20, s22
	s_add_i32 s1, s1, 0x8000
	s_cmp_lt_i32 s22, s16
	s_cselect_b32 s0, s0, s1
	s_cmp_lt_i32 s0, 0x8000
	s_cselect_b64 s[2:3], -1, 0
	s_cmpk_gt_i32 s0, 0x7fff
	s_mov_b64 s[10:11], -1
	s_cbranch_scc0 .Lrow1_1216
	s_add_i32 s4, s0, 0xffff8000
	s_lshl_b64 s[10:11], s[4:5], 12
	v_lshl_add_u64 v[46:47], v[160:161], 0, s[10:11]
	global_load_dwordx4 v[98:101], v[46:47], off
	global_load_dwordx4 v[58:61], v[46:47], off offset:1024
	global_load_dwordx4 v[54:57], v[46:47], off offset:2048
	s_nop 0
	global_load_dwordx4 v[46:49], v[46:47], off offset:3072
	s_mov_b64 s[10:11], 0

; DI void phase_e(const Ctx& C, int nslab, int has_post, int pl, int ps, float pw, int has_pre, int ql, int qs, int nrows,
;                 const GAS float* xsrc, const GAS float* csrc, GAS float* xdst, GAS float* cdst, bool xs16, bool xd16) {
;     ...
;         if (i + 16 < total) E_LOAD(i + 16, vM, yM);
.Lrow2_1213:
	s_mov_b64 s[98:99], 0
	s_cmp_ge_i32 s22, s17
	s_cbranch_scc1 .Lrow2_1220
	s_add_i32 s1, s21, s22
	s_add_i32 s0, s20, s22
	s_add_i32 s1, s1, 0x8000
	s_cmp_lt_i32 s22, s16
	s_cselect_b32 s0, s0, s1
	s_cmp_lt_i32 s0, 0x8000
	s_cselect_b64 s[2:3], -1, 0
	s_cmpk_gt_i32 s0, 0x7fff
	s_mov_b64 s[10:11], -1
	s_cbranch_scc0 .Lrow2_1216
	s_add_i32 s4, s0, 0xffff8000
	s_lshl_b64 s[10:11], s[4:5], 12
	v_lshl_add_u64 v[50:51], v[160:161], 0, s[10:11]
	global_load_dwordx4 v[34:37], v[50:51], off
	global_load_dwordx4 v[38:41], v[50:51], off offset:1024
	global_load_dwordx4 v[42:45], v[50:51], off offset:2048
	s_nop 0
	global_load_dwordx4 v[50:53], v[50:51], off offset:3072
	s_mov_b64 s[10:11], 0

; DI void phase_e(const Ctx& C, int nslab, int has_post, int pl, int ps, float pw, int has_pre, int ql, int qs, int nrows,
;                 const GAS float* xsrc, const GAS float* csrc, GAS float* xdst, GAS float* cdst, bool xs16, bool xd16) {
;     ...
;         if (i + 16 < total) E_LOAD(i + 16, vM, yM);
.Lrow1_1481:
	s_mov_b64 s[98:99], 0
	s_cmp_ge_i32 s23, s17
	s_cbranch_scc1 .Lrow1_1488
	s_add_i32 s1, s22, s23
	s_add_i32 s0, s21, s23
	s_add_i32 s1, s1, 0x8000
	s_cmp_lt_i32 s23, s16
	s_cselect_b32 s0, s0, s1
	s_cmp_lt_i32 s0, 0x8000
	s_cselect_b64 s[2:3], -1, 0
	s_cmpk_gt_i32 s0, 0x7fff
	s_mov_b64 s[10:11], -1
	s_cbranch_scc0 .Lrow1_1484
	s_add_i32 s4, s0, 0xffff8000
	s_lshl_b64 s[10:11], s[4:5], 12
	v_lshl_add_u64 v[46:47], v[160:161], 0, s[10:11]
	global_load_dwordx4 v[98:101], v[46:47], off
	global_load_dwordx4 v[58:61], v[46:47], off offset:1024
	global_load_dwordx4 v[54:57], v[46:47], off offset:2048
	s_nop 0
	global_load_dwordx4 v[46:49], v[46:47], off offset:3072
	s_mov_b64 s[10:11], 0

; #define GAS __attribute__((address_space(1)))
; DI void phase_e(const Ctx& C, int nslab, int has_post, int pl, int ps, float pw, int has_pre, int ql, int qs, int nrows,
;                 const GAS float* xsrc, const GAS float* csrc, GAS float* xdst, GAS float* cdst, bool xs16, bool xd16) {
;     ...
;     const int xpb = (MX + C.G - 1) / C.G, cpb = nrows > MX ? (MC + C.G - 1) / C.G : 0, total = xpb + cpb;
;     const GAS float* mod = WSP(float, WS_MOD); const GAS bf16* Y = WSP(bf16, WS_Y); const GAS bf16* YS = WSP(bf16, WS_YS); GAS bf16* H = WSP(bf16, WS_H);
;     f32x4 gpo[4], gpr[4], gt[4], sc[4], sh[4]; int cur = -1;
; #pragma unroll
;     for (int j = 0; j < 4; ++j) {
;         gpo[j] = has_post ? *(const GAS f32x4*)(INP(I_NPOST) + (pl * 3 + ps) * 1024 + 256 * j + 4 * lane) : (f32x4){0.f, 0.f, 0.f, 0.f};
;         gpr[j] = has_pre ? *(const GAS f32x4*)(INP(I_NPRE) + (ql * 3 + qs) * 1024 + 256 * j + 4 * lane) : (f32x4){0.f, 0.f, 0.f, 0.f};
;         gt[j] = sc[j] = sh[j] = (f32x4){0.f, 0.f, 0.f, 0.f};
;     }
;     f32x4 vN[4], vM[4]; u32x2 yN[4], yM[4];
;     ...
;     int i = C.wave;
;     if (i < total) E_LOAD(i, vN, yN);
.LBB0_2194:
	s_cmp_lt_i32 s78, 21
	s_cselect_b64 s[0:1], -1, 0
	s_cmp_gt_i32 s79, 20
	s_cselect_b64 s[2:3], -1, 0
	s_and_b64 s[0:1], s[0:1], s[2:3]
	s_andn2_b64 vcc, exec, s[0:1]
	s_cbranch_vccnz .LBB0_2275
	s_mov_b32 s4, 0
	s_mov_b32 s6, s62
	s_mov_b64 s[0:1], s[34:35]
	s_waitcnt vmcnt(1)
	v_mov_b32_e32 v38, v1
	s_mov_b32 s10, s63
	s_mov_b64 s[2:3], s[74:75]
	v_mov_b32_e32 v147, 0
	v_lshlrev_b32_e32 v2, 2, v38
	v_and_b32_e32 v66, 0xfc, v2
	v_lshlrev_b32_e32 v146, 2, v66
	v_lshl_add_u64 v[2:3], s[50:51], 0, v[146:147]
	s_movk_i32 s4, 0x4000
	v_add_co_u32_e32 v34, vcc, s4, v2
	s_movk_i32 s4, 0x5000
	s_nop 0
	v_addc_co_u32_e32 v35, vcc, 0, v3, vcc
	v_lshl_add_u64 v[2:3], s[48:49], 0, v[146:147]
	v_add_co_u32_e32 v36, vcc, s4, v2
	v_readfirstlane_b32 s4, v38
	s_nop 0
	v_addc_co_u32_e32 v37, vcc, 0, v3, vcc
	global_load_dwordx4 v[2:5], v[34:35], off
	global_load_dwordx4 v[6:9], v[34:35], off offset:1024
	global_load_dwordx4 v[10:13], v[36:37], off
	global_load_dwordx4 v[14:17], v[36:37], off offset:1024
	global_load_dwordx4 v[18:21], v[34:35], off offset:2048
	global_load_dwordx4 v[22:25], v[34:35], off offset:3072
	global_load_dwordx4 v[26:29], v[36:37], off offset:2048
	global_load_dwordx4 v[30:33], v[36:37], off offset:3072
	s_ashr_i32 s16, s4, 6
	s_add_u32 s4, s0, 0x600000
	s_addc_u32 s5, s1, 0
	s_abs_i32 s7, s6
	v_cvt_f32_u32_e32 v34, s7
	s_sub_i32 s9, 0, s7
	s_add_i32 s8, s6, 0x7fff
	s_xor_b32 s6, s8, s6
	v_rcp_iflag_f32_e32 v34, v34
	s_abs_i32 s8, s8
	s_ashr_i32 s6, s6, 31
	v_mul_f32_e32 v34, 0x4f7ffffe, v34
	v_cvt_u32_f32_e32 v34, v34
	s_nop 0
	v_readfirstlane_b32 s11, v34
	s_mul_i32 s9, s9, s11
	s_mul_hi_u32 s9, s11, s9
	s_add_i32 s11, s11, s9
	s_mul_hi_u32 s9, s8, s11
	s_mul_i32 s11, s9, s7
	s_sub_i32 s8, s8, s11
	s_add_i32 s11, s9, 1
	s_sub_i32 s12, s8, s7
	s_cmp_ge_u32 s8, s7
	s_cselect_b32 s9, s11, s9
	s_cselect_b32 s8, s12, s8
	s_add_i32 s11, s9, 1
	s_cmp_ge_u32 s8, s7
	s_cselect_b32 s7, s11, s9
	s_xor_b32 s7, s7, s6
	s_sub_i32 s17, s7, s6
	s_add_u32 s6, s0, 0xa200000
	s_addc_u32 s7, s1, 0
	s_cmp_lt_i32 s16, s17
	s_cselect_b64 s[8:9], -1, 0
	s_cmp_ge_i32 s16, s17
	s_mul_i32 s18, s17, s10
	s_cbranch_scc1 .LBB0_2198
	s_add_i32 s12, s18, s16
	s_cmpk_gt_i32 s12, 0x7fff
	s_cbranch_scc0 .LBB0_2200
	s_add_i32 s10, s12, 0xffff8000
	s_mov_b32 s11, 0
	s_lshl_b64 s[14:15], s[10:11], 12
	s_add_u32 s14, s4, s14
	s_addc_u32 s15, s5, s15
	global_load_dwordx4 v[62:65], v146, s[14:15]
	global_load_dwordx4 v[58:61], v146, s[14:15] offset:1024
	global_load_dwordx4 v[54:57], v146, s[14:15] offset:2048
	global_load_dwordx4 v[50:53], v146, s[14:15] offset:3072
	s_mov_b32 s13, s11
	s_lshl_b64 s[10:11], s[12:13], 11
	s_cbranch_execz .LBB0_2201
	s_branch .LBB0_2202

; DI void phase_e(const Ctx& C, int nslab, int has_post, int pl, int ps, float pw, int has_pre, int ql, int qs, int nrows,
;                 const GAS float* xsrc, const GAS float* csrc, GAS float* xdst, GAS float* cdst, bool xs16, bool xd16) {
;     ...
;     if (i + 8 < total) E_LOAD(i + 8, vM, yM);
.LBB0_2203:
	s_add_i32 s12, s18, s10
	s_cmpk_gt_i32 s12, 0x7fff
	s_cbranch_scc0 .LBB0_2205
	s_add_i32 s10, s12, 0xffff8000
	s_mov_b32 s11, 0
	s_lshl_b64 s[14:15], s[10:11], 12
	s_add_u32 s14, s4, s14
	s_addc_u32 s15, s5, s15
	global_load_dwordx4 v[34:37], v146, s[14:15]
	global_load_dwordx4 v[38:41], v146, s[14:15] offset:1024
	global_load_dwordx4 v[42:45], v146, s[14:15] offset:2048
	global_load_dwordx4 v[46:49], v146, s[14:15] offset:3072
	s_mov_b32 s13, s11
	s_lshl_b64 s[10:11], s[12:13], 11
	s_cbranch_execz .LBB0_2206
	s_branch .LBB0_2207

; DI void phase_e(const Ctx& C, int nslab, int has_post, int pl, int ps, float pw, int has_pre, int ql, int qs, int nrows,
;                 const GAS float* xsrc, const GAS float* csrc, GAS float* xdst, GAS float* cdst, bool xs16, bool xd16) {
;     ...
;         if (i + 16 < total) E_LOAD(i + 16, vM, yM);
.LBB0_2210:
	s_mov_b64 s[98:99], 0
	s_add_i32 s6, s18, s16
	s_add_i32 s0, s16, 16
	s_cmp_ge_i32 s0, s17
	s_cbranch_scc1 .LBB0_2216
	s_add_i32 s10, s6, 16
	s_cmpk_gt_i32 s10, 0x7fff
	s_mov_b64 s[12:13], -1
	s_cbranch_scc0 .LBB0_2213
	s_add_i32 s0, s6, 0xffff8010
	s_lshl_b64 s[8:9], s[0:1], 12
	v_lshl_add_u64 v[126:127], v[164:165], 0, s[8:9]
	global_load_dwordx4 v[114:117], v[126:127], off
	global_load_dwordx4 v[118:121], v[126:127], off offset:1024
	global_load_dwordx4 v[122:125], v[126:127], off offset:2048
	s_nop 0
	global_load_dwordx4 v[126:129], v[126:127], off offset:3072
	s_mov_b32 s11, s1
	s_lshl_b64 s[8:9], s[10:11], 11
	s_mov_b64 s[12:13], 0

; DI void phase_e(const Ctx& C, int nslab, int has_post, int pl, int ps, float pw, int has_pre, int ql, int qs, int nrows,
;                 const GAS float* xsrc, const GAS float* csrc, GAS float* xdst, GAS float* cdst, bool xs16, bool xd16) {
;     ...
;         if (i + 16 < total) E_LOAD(i + 16, vM, yM);
.Lrow1_2210:
	s_mov_b64 s[98:99], 0
	s_add_i32 s6, s18, s16
	s_add_i32 s0, s16, 16
	s_cmp_ge_i32 s0, s17
	s_cbranch_scc1 .Lrow1_2216
	s_add_i32 s10, s6, 16
	s_cmpk_gt_i32 s10, 0x7fff
	s_mov_b64 s[12:13], -1
	s_cbranch_scc0 .Lrow1_2213
	s_add_i32 s0, s6, 0xffff8010
	s_lshl_b64 s[8:9], s[0:1], 12
	v_lshl_add_u64 v[50:51], v[164:165], 0, s[8:9]
	global_load_dwordx4 v[62:65], v[50:51], off
	global_load_dwordx4 v[58:61], v[50:51], off offset:1024
	global_load_dwordx4 v[54:57], v[50:51], off offset:2048
	s_nop 0
	global_load_dwordx4 v[50:53], v[50:51], off offset:3072
	s_mov_b32 s11, s1
	s_lshl_b64 s[8:9], s[10:11], 11
	s_mov_b64 s[12:13], 0

; DI void phase_e(const Ctx& C, int nslab, int has_post, int pl, int ps, float pw, int has_pre, int ql, int qs, int nrows,
;                 const GAS float* xsrc, const GAS float* csrc, GAS float* xdst, GAS float* cdst, bool xs16, bool xd16) {
;     ...
;         if (i + 16 < total) E_LOAD(i + 16, vM, yM);
.Lrow2_2210:
	s_mov_b64 s[98:99], 0
	s_add_i32 s6, s18, s16
	s_add_i32 s0, s16, 16
	s_cmp_ge_i32 s0, s17
	s_cbranch_scc1 .Lrow2_2216
	s_add_i32 s10, s6, 16
	s_cmpk_gt_i32 s10, 0x7fff
	s_mov_b64 s[12:13], -1
	s_cbranch_scc0 .Lrow2_2213
	s_add_i32 s0, s6, 0xffff8010
	s_lshl_b64 s[8:9], s[0:1], 12
	v_lshl_add_u64 v[46:47], v[164:165], 0, s[8:9]
	global_load_dwordx4 v[34:37], v[46:47], off
	global_load_dwordx4 v[38:41], v[46:47], off offset:1024
	global_load_dwordx4 v[42:45], v[46:47], off offset:2048
	s_nop 0
	global_load_dwordx4 v[46:49], v[46:47], off offset:3072
	s_mov_b32 s11, s1
	s_lshl_b64 s[8:9], s[10:11], 11
	s_mov_b64 s[12:13], 0

; #define GAS __attribute__((address_space(1)))
; DI void phase_e(const Ctx& C, int nslab, int has_post, int pl, int ps, float pw, int has_pre, int ql, int qs, int nrows,
;                 const GAS float* xsrc, const GAS float* csrc, GAS float* xdst, GAS float* cdst, bool xs16, bool xd16) {
;     ...
;     const int xpb = (MX + C.G - 1) / C.G, cpb = nrows > MX ? (MC + C.G - 1) / C.G : 0, total = xpb + cpb;
;     const GAS float* mod = WSP(float, WS_MOD); const GAS bf16* Y = WSP(bf16, WS_Y); const GAS bf16* YS = WSP(bf16, WS_YS); GAS bf16* H = WSP(bf16, WS_H);
;     f32x4 gpo[4], gpr[4], gt[4], sc[4], sh[4]; int cur = -1;
; #pragma unroll
;     for (int j = 0; j < 4; ++j) {
;         gpo[j] = has_post ? *(const GAS f32x4*)(INP(I_NPOST) + (pl * 3 + ps) * 1024 + 256 * j + 4 * lane) : (f32x4){0.f, 0.f, 0.f, 0.f};
;         gpr[j] = has_pre ? *(const GAS f32x4*)(INP(I_NPRE) + (ql * 3 + qs) * 1024 + 256 * j + 4 * lane) : (f32x4){0.f, 0.f, 0.f, 0.f};
;         gt[j] = sc[j] = sh[j] = (f32x4){0.f, 0.f, 0.f, 0.f};
;     }
;     f32x4 vN[4], vM[4]; u32x2 yN[4], yM[4];
;     ...
;     int i = C.wave;
;     if (i < total) E_LOAD(i, vN, yN);
.LBB0_2427:
	s_cmp_lt_i32 s78, 24
	s_cselect_b64 s[0:1], -1, 0
	s_cmp_gt_i32 s79, 23
	s_cselect_b64 s[2:3], -1, 0
	s_and_b64 s[0:1], s[0:1], s[2:3]
	s_andn2_b64 vcc, exec, s[0:1]
	s_cbranch_vccnz .LBB0_2431
	s_mov_b32 s0, 0
	s_waitcnt vmcnt(0)
	v_mov_b32_e32 v20, v1
	v_mov_b32_e32 v83, 0
	v_lshlrev_b32_e32 v2, 2, v20
	v_and_b32_e32 v50, 0xfc, v2
	v_lshlrev_b32_e32 v82, 2, v50
	v_lshl_add_u64 v[2:3], s[50:51], 0, v[82:83]
	v_add_co_u32_e32 v18, vcc, 0x5000, v2
	v_readfirstlane_b32 s0, v20
	s_nop 0
	v_addc_co_u32_e32 v19, vcc, 0, v3, vcc
	global_load_dwordx4 v[2:5], v[18:19], off
	global_load_dwordx4 v[6:9], v[18:19], off offset:1024
	global_load_dwordx4 v[10:13], v[18:19], off offset:2048
	global_load_dwordx4 v[14:17], v[18:19], off offset:3072
	s_ashr_i32 s14, s0, 6
	s_add_u32 s0, s34, 0x600000
	s_addc_u32 s1, s35, 0
	s_add_u32 s2, s34, 0x19a00000
	s_addc_u32 s3, s35, 0
	s_abs_i32 s4, s62
	v_cvt_f32_u32_e32 v18, s4
	s_sub_i32 s7, 0, s4
	s_add_i32 s5, s62, 0x7fff
	s_xor_b32 s6, s5, s62
	v_rcp_iflag_f32_e32 v18, v18
	s_abs_i32 s5, s5
	s_ashr_i32 s6, s6, 31
	v_mul_f32_e32 v18, 0x4f7ffffe, v18
	v_cvt_u32_f32_e32 v18, v18
	s_nop 0
	v_readfirstlane_b32 s8, v18
	s_mul_i32 s7, s7, s8
	s_mul_hi_u32 s7, s8, s7
	s_add_i32 s8, s8, s7
	s_mul_hi_u32 s7, s5, s8
	s_mul_i32 s8, s7, s4
	s_sub_i32 s5, s5, s8
	s_add_i32 s8, s7, 1
	s_sub_i32 s9, s5, s4
	s_cmp_ge_u32 s5, s4
	s_cselect_b32 s7, s8, s7
	s_cselect_b32 s5, s9, s5
	s_add_i32 s8, s7, 1
	s_cmp_ge_u32 s5, s4
	s_cselect_b32 s4, s8, s7
	s_xor_b32 s4, s4, s6
	s_sub_i32 s15, s4, s6
	s_add_u32 s4, s34, 0xa200000
	s_addc_u32 s5, s35, 0
	s_cmp_lt_i32 s14, s15
	s_cselect_b64 s[6:7], -1, 0
	s_cmp_ge_i32 s14, s15
	s_mul_i32 s16, s15, s63
	s_cbranch_scc1 .LBB0_2433
	s_add_i32 s10, s16, s14
	s_cmpk_gt_i32 s10, 0x7fff
	s_cbranch_scc0 .LBB0_2435
	s_add_i32 s8, s10, 0xffff8000
	s_mov_b32 s9, 0
	s_lshl_b64 s[12:13], s[8:9], 12
	s_add_u32 s12, s0, s12
	s_addc_u32 s13, s1, s13
	global_load_dwordx4 v[30:33], v82, s[12:13]
	global_load_dwordx4 v[26:29], v82, s[12:13] offset:1024
	global_load_dwordx4 v[22:25], v82, s[12:13] offset:2048
	global_load_dwordx4 v[18:21], v82, s[12:13] offset:3072
	s_mov_b32 s11, s9
	s_lshl_b64 s[8:9], s[10:11], 11
	s_cbranch_execz .LBB0_2436
	s_branch .LBB0_2437

; DI void phase_e(const Ctx& C, int nslab, int has_post, int pl, int ps, float pw, int has_pre, int ql, int qs, int nrows,
;                 const GAS float* xsrc, const GAS float* csrc, GAS float* xdst, GAS float* cdst, bool xs16, bool xd16) {
;     ...
;     if (i + 8 < total) E_LOAD(i + 8, vM, yM);
.LBB0_2438:
	s_add_i32 s10, s16, s8
	s_cmpk_gt_i32 s10, 0x7fff
	s_cbranch_scc0 .LBB0_2440
	s_add_i32 s8, s10, 0xffff8000
	s_mov_b32 s9, 0
	s_lshl_b64 s[12:13], s[8:9], 12
	s_add_u32 s12, s0, s12
	s_addc_u32 s13, s1, s13
	global_load_dwordx4 v[34:37], v82, s[12:13]
	global_load_dwordx4 v[38:41], v82, s[12:13] offset:1024
	global_load_dwordx4 v[42:45], v82, s[12:13] offset:2048
	global_load_dwordx4 v[46:49], v82, s[12:13] offset:3072
	s_mov_b32 s11, s9
	s_lshl_b64 s[8:9], s[10:11], 11
	s_cbranch_execz .LBB0_2441
	s_branch .LBB0_2442

; DI void phase_e(const Ctx& C, int nslab, int has_post, int pl, int ps, float pw, int has_pre, int ql, int qs, int nrows,
;                 const GAS float* xsrc, const GAS float* csrc, GAS float* xdst, GAS float* cdst, bool xs16, bool xd16) {
;     ...
;         if (i + 16 < total) E_LOAD(i + 16, vM, yM);
.LBB0_2445:
	s_mov_b64 s[98:99], 0
	s_add_i32 s19, s16, s14
	s_add_i32 s2, s14, 16
	s_cmp_ge_i32 s2, s15
	s_cbranch_scc1 .LBB0_2451
	s_add_i32 s8, s19, 16
	s_cmpk_gt_i32 s8, 0x7fff
	s_mov_b64 s[10:11], -1
	s_cbranch_scc0 .LBB0_2448
	s_add_i32 s2, s19, 0xffff8010
	s_lshl_b64 s[6:7], s[2:3], 12
	v_lshl_add_u64 v[106:107], v[104:105], 0, s[6:7]
	global_load_dwordx4 v[66:69], v[106:107], off
	global_load_dwordx4 v[70:73], v[106:107], off offset:1024
	global_load_dwordx4 v[74:77], v[106:107], off offset:2048
	global_load_dwordx4 v[78:81], v[106:107], off offset:3072
	s_mov_b32 s9, s3
	s_lshl_b64 s[6:7], s[8:9], 11
	s_mov_b64 s[10:11], 0

; DI void phase_e(const Ctx& C, int nslab, int has_post, int pl, int ps, float pw, int has_pre, int ql, int qs, int nrows,
;                 const GAS float* xsrc, const GAS float* csrc, GAS float* xdst, GAS float* cdst, bool xs16, bool xd16) {
;     ...
;         if (i + 16 < total) E_LOAD(i + 16, vM, yM);
.Lrow1_2445:
	s_mov_b64 s[98:99], 0
	s_add_i32 s19, s16, s14
	s_add_i32 s2, s14, 16
	s_cmp_ge_i32 s2, s15
	s_cbranch_scc1 .Lrow1_2451
	s_add_i32 s8, s19, 16
	s_cmpk_gt_i32 s8, 0x7fff
	s_mov_b64 s[10:11], -1
	s_cbranch_scc0 .Lrow1_2448
	s_add_i32 s2, s19, 0xffff8010
	s_lshl_b64 s[6:7], s[2:3], 12
	v_lshl_add_u64 v[98:99], v[104:105], 0, s[6:7]
	global_load_dwordx4 v[30:33], v[98:99], off
	global_load_dwordx4 v[26:29], v[98:99], off offset:1024
	global_load_dwordx4 v[22:25], v[98:99], off offset:2048
	global_load_dwordx4 v[18:21], v[98:99], off offset:3072
	s_mov_b32 s9, s3
	s_lshl_b64 s[6:7], s[8:9], 11
	s_mov_b64 s[10:11], 0

; DI void phase_e(const Ctx& C, int nslab, int has_post, int pl, int ps, float pw, int has_pre, int ql, int qs, int nrows,
;                 const GAS float* xsrc, const GAS float* csrc, GAS float* xdst, GAS float* cdst, bool xs16, bool xd16) {
;     ...
;         if (i + 16 < total) E_LOAD(i + 16, vM, yM);
.Lrow2_2445:
	s_mov_b64 s[98:99], 0
	s_add_i32 s19, s16, s14
	s_add_i32 s2, s14, 16
	s_cmp_ge_i32 s2, s15
	s_cbranch_scc1 .Lrow2_2451
	s_add_i32 s8, s19, 16
	s_cmpk_gt_i32 s8, 0x7fff
	s_mov_b64 s[10:11], -1
	s_cbranch_scc0 .Lrow2_2448
	s_add_i32 s2, s19, 0xffff8010
	s_lshl_b64 s[6:7], s[2:3], 12
	v_lshl_add_u64 v[88:89], v[104:105], 0, s[6:7]
	global_load_dwordx4 v[34:37], v[88:89], off
	global_load_dwordx4 v[38:41], v[88:89], off offset:1024
	global_load_dwordx4 v[42:45], v[88:89], off offset:2048
	global_load_dwordx4 v[46:49], v[88:89], off offset:3072
	s_mov_b32 s9, s3
	s_lshl_b64 s[6:7], s[8:9], 11
	s_mov_b64 s[10:11], 0
